# prologue loops batched plus attention bias-table preload batched into one round trip (8 loads, one wait); dead padding keeps loop alignment
# speedup vs baseline: 1.0148x; 1.0148x over previous
; #define LAS __attribute__((address_space(3)))
; __device__ __forceinline__ void transpose_item(const float* W, int K, int N, const float* g0, const float* g1, bf16_t* WT, LAS unsigned* T, int item, int lane, bool gate_up_interleave = false, bool rope_heads = false) {
;     ...
;     const int c = lane & 7;
; #pragma unroll 4
;     for (int it = 0; it < 16; ++it) {
;         const int n = 8 * it + (lane >> 3);
;         const u32x4 o = *(const LAS u32x4*)(T + n * PD + 4 * c);
;         const int nd = (rope_heads && nb >= 24 && nb < 34) ? ((n < 64) ? (8 * (n >> 2) + (n & 3)) : (8 * ((n - 64) >> 2) + 4 + (n & 3))) : n;
;         *(u32x4*)(WT + (size_t)(dn0 + nd) * K + k0 + 8 * c) = o;
;     }
.LBB0_46:
	s_andn2_b64 vcc, exec, s[4:5]
	s_cbranch_vccnz .LBB0_25
	v_add_u32_e32 v6, 48, v21
	v_and_or_b32 v6, v6, s28, v27
	s_branch .LBB0_25
	s_nop 0
	s_nop 0
	s_nop 0
	s_nop 0
	s_nop 0
	s_nop 0
	s_nop 0
	s_nop 0
	s_nop 0
	s_nop 0
	s_nop 0
	s_nop 0
	s_nop 0
	s_nop 0
	s_nop 0
	s_nop 0
	s_nop 0
	s_nop 0

; #define LAS __attribute__((address_space(3)))
; __global__ void __launch_bounds__(NTHREADS, 2) fwd_kernel(Args a) {
;     ...
;             LAS float* rpl = (LAS float*)(lds + 4096 + wave * 4096 + 256);
;             const int ql = lane & 31, hi = lane >> 5, w = wave;
;             {
;                 const float* rp = rpb + ((size_t)layer * 8 + w) * (15 * 31);
;                 for (int i = lane; i < 15 * 31; i += 64) rpl[i] = rp[i] * LOG2E;
;                 asm volatile("s_waitcnt lgkmcnt(0)" ::: "memory");
.LBB0_133:
	s_cmp_gt_i32 s16, 0
	s_mov_b64 s[10:11], -1
	s_cbranch_scc0 .LBB0_168
	v_readlane_b32 s60, v238, 0
	s_lshl_b32 s14, s50, 3
	v_readlane_b32 s8, v238, 20
	v_readlane_b32 s64, v238, 4
	v_readlane_b32 s65, v238, 5
	s_add_i32 s14, s14, s8
	v_readlane_b32 s66, v238, 6
	v_readlane_b32 s67, v238, 7
	v_readlane_b32 s68, v238, 8
	v_readlane_b32 s69, v238, 9
	v_readlane_b32 s70, v238, 10
	v_readlane_b32 s71, v238, 11
	v_readlane_b32 s72, v238, 12
	v_readlane_b32 s73, v238, 13
	v_readlane_b32 s74, v238, 14
	v_readlane_b32 s75, v238, 15
	s_mov_b64 s[20:21], s[64:65]
	s_mul_i32 s10, s14, 0x744
	s_mov_b64 s[28:29], s[72:73]
	v_and_b32_e32 v193, 63, v206
	s_mul_hi_u32 s11, s14, 0x744
	s_add_u32 s10, s28, s10
	s_addc_u32 s11, s29, s11
	v_lshlrev_b32_e32 v0, 2, v193
	global_load_dword v2, v0, s[10:11]
	global_load_dword v4, v0, s[10:11] offset:256
	global_load_dword v226, v0, s[10:11] offset:512
	global_load_dword v227, v0, s[10:11] offset:768
	global_load_dword v228, v0, s[10:11] offset:1024
	global_load_dword v229, v0, s[10:11] offset:1280
	global_load_dword v230, v0, s[10:11] offset:1536
	s_movk_i32 s12, 0x191
	v_readlane_b32 s61, v238, 1
	v_readlane_b32 s62, v238, 2
	v_readlane_b32 s63, v238, 3
	s_mov_b64 s[22:23], s[66:67]
	s_mov_b64 s[24:25], s[68:69]
	s_mov_b64 s[26:27], s[70:71]
	s_mov_b64 s[30:31], s[74:75]
	v_or_b32_e32 v3, 0x180, v193
	v_cmp_gt_u32_e32 vcc, s12, v3
	s_and_saveexec_b64 s[12:13], vcc
	global_load_dword v231, v0, s[10:11] offset:1792
	s_or_b64 exec, exec, s[12:13]
	s_waitcnt vmcnt(0)
	v_mul_f32_e32 v3, 0x3fb8aa3b, v2
	v_add_u32_e32 v2, s33, v0
	v_mul_f32_e32 v4, 0x3fb8aa3b, v4
	ds_write2st64_b32 v2, v3, v4 offset0:17 offset1:18
	v_mul_f32_e32 v226, 0x3fb8aa3b, v226
	v_mul_f32_e32 v227, 0x3fb8aa3b, v227
	ds_write2st64_b32 v2, v226, v227 offset0:19 offset1:20
	v_mul_f32_e32 v228, 0x3fb8aa3b, v228
	v_mul_f32_e32 v229, 0x3fb8aa3b, v229
	ds_write2st64_b32 v2, v228, v229 offset0:21 offset1:22
	v_mul_f32_e32 v230, 0x3fb8aa3b, v230
	ds_write_b32 v2, v230 offset:5888
	s_and_saveexec_b64 s[12:13], vcc
	s_cbranch_execz .LBB0_136
	v_mul_f32_e32 v231, 0x3fb8aa3b, v231
	ds_write_b32 v2, v231 offset:6144
